# P0 weight-transpose loops: the 4 global loads of a tile issued back to back (one wait) instead of load/wait/LDS-write x4
# baseline (speedup 1.0000x reference)
.LBB0_28:
	s_or_b64 exec, exec, s[4:5]
	s_waitcnt vmcnt(0)
	s_waitcnt lgkmcnt(0)
	s_barrier
	ds_read2_b32 v[4:5], v15 offset1:32
	ds_read2_b32 v[10:11], v15 offset0:65 offset1:97
	ds_read2_b32 v[24:25], v15 offset0:130 offset1:162
	ds_read2_b32 v[26:27], v15 offset0:195 offset1:227
	ds_read2_b32 v[28:29], v23 offset0:4 offset1:36
	ds_read2_b32 v[30:31], v23 offset0:69 offset1:101
	ds_read2_b32 v[32:33], v23 offset0:134 offset1:166
	ds_read2_b32 v[34:35], v23 offset0:199 offset1:231
	s_sub_i32 s4, 0, s16
	s_add_i32 s4, s10, s4
	v_add_u32_e32 v38, s8, v14
	s_ashr_i32 s5, s4, 31
	v_ashrrev_i32_e32 v39, 31, v38
	v_lshl_add_u64 v[36:37], s[4:5], 1, v[8:9]
	v_lshlrev_b64 v[40:41], 12, v[38:39]
	s_waitcnt lgkmcnt(6)
	v_cvt_pk_bf16_f32 v0, v4, v10
	s_waitcnt lgkmcnt(4)
	v_cvt_pk_bf16_f32 v1, v24, v26
	s_waitcnt lgkmcnt(2)
	v_cvt_pk_bf16_f32 v2, v28, v30
	s_waitcnt lgkmcnt(0)
	v_cvt_pk_bf16_f32 v3, v32, v34
	v_lshl_add_u64 v[40:41], v[36:37], 0, v[40:41]
	v_add_u32_e32 v4, 32, v38
	global_store_dwordx4 v[40:41], v[0:3], off
	s_add_i32 s15, s15, s3
	s_add_i32 s10, s10, s11
	v_cvt_pk_bf16_f32 v0, v5, v11
	v_ashrrev_i32_e32 v5, 31, v4
	v_lshlrev_b64 v[4:5], 12, v[4:5]
	v_cvt_pk_bf16_f32 v1, v25, v27
	v_cvt_pk_bf16_f32 v2, v29, v31
	v_cvt_pk_bf16_f32 v3, v33, v35
	v_lshl_add_u64 v[4:5], v[36:37], 0, v[4:5]
	s_cmpk_lt_i32 s15, 0x1040
	global_store_dwordx4 v[4:5], v[0:3], off
	s_cbranch_scc0 .LBB0_37
.LBB0_29:
	s_ashr_i32 s4, s15, 31
	s_lshr_b32 s4, s4, 27
	s_add_i32 s4, s15, s4
	s_ashr_i32 s4, s4, 5
	s_lshl_b32 s16, s4, 11
	s_lshl_b32 s8, s4, 6
	s_sub_i32 s4, s10, s16
	v_or_b32_e32 v0, s8, v13
	v_add_u32_e32 v24, s4, v12
	v_cmp_gt_i32_e32 vcc, s12, v0
	s_ashr_i32 s9, s8, 31
	v_cmp_gt_i32_e64 s[4:5], s13, v24
	v_lshl_add_u64 v[10:11], s[8:9], 2, v[6:7]
	s_and_b64 s[18:19], s[4:5], vcc
	v_mov_b32_e32 v0, 0
	v_mov_b32_e32 v1, 0
	v_mov_b32_e32 v2, 0
	v_mov_b32_e32 v3, 0
	s_barrier
	v_mov_b32_e32 v64, 0
	v_mov_b32_e32 v65, 0
	v_mov_b32_e32 v66, 0
	v_mov_b32_e32 v67, 0
	s_and_saveexec_b64 s[4:5], s[18:19]
	v_mad_i64_i32 v[84:85], s[18:19], v24, s14, v[10:11]
	global_load_dwordx4 v[64:67], v[84:85], off
	s_or_b64 exec, exec, s[4:5]
	v_add_u32_e32 v81, 16, v24
	v_cmp_gt_i32_e64 s[4:5], s13, v81
	s_and_b64 s[18:19], s[4:5], vcc
	v_mov_b32_e32 v68, 0
	v_mov_b32_e32 v69, 0
	v_mov_b32_e32 v70, 0
	v_mov_b32_e32 v71, 0
	s_and_saveexec_b64 s[4:5], s[18:19]
	v_mad_i64_i32 v[84:85], s[18:19], v81, s14, v[10:11]
	global_load_dwordx4 v[68:71], v[84:85], off
	s_or_b64 exec, exec, s[4:5]
	v_add_u32_e32 v82, 32, v24
	v_cmp_gt_i32_e64 s[4:5], s13, v82
	s_and_b64 s[18:19], s[4:5], vcc
	v_mov_b32_e32 v72, 0
	v_mov_b32_e32 v73, 0
	v_mov_b32_e32 v74, 0
	v_mov_b32_e32 v75, 0
	s_and_saveexec_b64 s[4:5], s[18:19]
	v_mad_i64_i32 v[84:85], s[18:19], v82, s14, v[10:11]
	global_load_dwordx4 v[72:75], v[84:85], off
	s_or_b64 exec, exec, s[4:5]
	v_add_u32_e32 v83, 48, v24
	v_cmp_gt_i32_e64 s[4:5], s13, v83
	s_and_b64 s[18:19], s[4:5], vcc
	v_mov_b32_e32 v76, 0
	v_mov_b32_e32 v77, 0
	v_mov_b32_e32 v78, 0
	v_mov_b32_e32 v79, 0
	s_and_saveexec_b64 s[4:5], s[18:19]
	v_mad_i64_i32 v[84:85], s[18:19], v83, s14, v[10:11]
	global_load_dwordx4 v[76:79], v[84:85], off
	s_or_b64 exec, exec, s[4:5]
	s_waitcnt vmcnt(0)
	ds_write2_b32 v16, v64, v65 offset1:1
	ds_write2_b32 v16, v66, v67 offset0:2 offset1:3
	ds_write2_b32 v17, v68, v69 offset1:1
	ds_write2_b32 v18, v70, v71 offset1:1
	ds_write2_b32 v19, v72, v73 offset1:1
	ds_write2_b32 v20, v74, v75 offset1:1
	ds_write2_b32 v21, v76, v77 offset1:1
	ds_write2_b32 v22, v78, v79 offset1:1
	s_branch .LBB0_28

.LBB0_39:
	s_or_b64 exec, exec, s[4:5]
	s_waitcnt vmcnt(0)
	s_waitcnt lgkmcnt(0)
	s_barrier
	ds_read2_b32 v[4:5], v19 offset1:32
	ds_read2_b32 v[10:11], v19 offset0:65 offset1:97
	ds_read2_b32 v[12:13], v19 offset0:130 offset1:162
	ds_read2_b32 v[14:15], v19 offset0:195 offset1:227
	ds_read2_b32 v[28:29], v27 offset0:4 offset1:36
	ds_read2_b32 v[30:31], v27 offset0:69 offset1:101
	ds_read2_b32 v[32:33], v27 offset0:134 offset1:166
	ds_read2_b32 v[34:35], v27 offset0:199 offset1:231
	s_sub_i32 s4, 0, s14
	s_add_i32 s4, s11, s4
	v_add_u32_e32 v38, s8, v18
	s_ashr_i32 s5, s4, 31
	v_ashrrev_i32_e32 v39, 31, v38
	v_lshl_add_u64 v[36:37], s[4:5], 1, v[8:9]
	v_lshlrev_b64 v[40:41], 12, v[38:39]
	s_waitcnt lgkmcnt(6)
	v_cvt_pk_bf16_f32 v0, v4, v10
	s_waitcnt lgkmcnt(4)
	v_cvt_pk_bf16_f32 v1, v12, v14
	s_waitcnt lgkmcnt(2)
	v_cvt_pk_bf16_f32 v2, v28, v30
	s_waitcnt lgkmcnt(0)
	v_cvt_pk_bf16_f32 v3, v32, v34
	v_lshl_add_u64 v[40:41], v[36:37], 0, v[40:41]
	v_add_u32_e32 v4, 32, v38
	global_store_dwordx4 v[40:41], v[0:3], off
	s_add_i32 s10, s10, s3
	s_add_i32 s11, s11, s12
	v_cvt_pk_bf16_f32 v0, v5, v11
	v_ashrrev_i32_e32 v5, 31, v4
	v_lshlrev_b64 v[4:5], 12, v[4:5]
	v_cvt_pk_bf16_f32 v1, v13, v15
	v_cvt_pk_bf16_f32 v2, v29, v31
	v_cvt_pk_bf16_f32 v3, v33, v35
	v_lshl_add_u64 v[4:5], v[36:37], 0, v[4:5]
	s_cmpk_lt_i32 s10, 0x400
	global_store_dwordx4 v[4:5], v[0:3], off
	s_cbranch_scc0 .LBB0_48
.LBB0_40:
	s_ashr_i32 s4, s10, 31
	s_lshr_b32 s4, s4, 27
	s_add_i32 s4, s10, s4
	s_ashr_i32 s4, s4, 5
	s_lshl_b32 s14, s4, 11
	s_lshl_b32 s8, s4, 6
	s_sub_i32 s4, s11, s14
	v_or_b32_e32 v0, s8, v17
	v_add_u32_e32 v12, s4, v16
	v_cmp_gt_i32_e32 vcc, s13, v0
	s_ashr_i32 s9, s8, 31
	v_cmp_gt_i32_e64 s[4:5], s13, v12
	v_lshl_add_u64 v[10:11], s[8:9], 2, v[6:7]
	s_and_b64 s[16:17], s[4:5], vcc
	v_mov_b32_e32 v0, 0
	v_mov_b32_e32 v1, 0
	v_mov_b32_e32 v2, 0
	v_mov_b32_e32 v3, 0
	s_barrier
	v_mov_b32_e32 v64, 0
	v_mov_b32_e32 v65, 0
	v_mov_b32_e32 v66, 0
	v_mov_b32_e32 v67, 0
	s_and_saveexec_b64 s[4:5], s[16:17]
	v_mov_b32_e32 v86, v12
	v_ashrrev_i32_e32 v87, 31, v86
	v_lshlrev_b64 v[84:85], 13, v[86:87]
	v_lshl_add_u64 v[84:85], v[10:11], 0, v[84:85]
	global_load_dwordx4 v[64:67], v[84:85], off
	s_or_b64 exec, exec, s[4:5]
	v_add_u32_e32 v81, 16, v12
	v_cmp_gt_i32_e64 s[4:5], s13, v81
	s_and_b64 s[16:17], s[4:5], vcc
	v_mov_b32_e32 v68, 0
	v_mov_b32_e32 v69, 0
	v_mov_b32_e32 v70, 0
	v_mov_b32_e32 v71, 0
	s_and_saveexec_b64 s[4:5], s[16:17]
	v_mov_b32_e32 v86, v81
	v_ashrrev_i32_e32 v87, 31, v86
	v_lshlrev_b64 v[84:85], 13, v[86:87]
	v_lshl_add_u64 v[84:85], v[10:11], 0, v[84:85]
	global_load_dwordx4 v[68:71], v[84:85], off
	s_or_b64 exec, exec, s[4:5]
	v_add_u32_e32 v82, 32, v12
	v_cmp_gt_i32_e64 s[4:5], s13, v82
	s_and_b64 s[16:17], s[4:5], vcc
	v_mov_b32_e32 v72, 0
	v_mov_b32_e32 v73, 0
	v_mov_b32_e32 v74, 0
	v_mov_b32_e32 v75, 0
	s_and_saveexec_b64 s[4:5], s[16:17]
	v_mov_b32_e32 v86, v82
	v_ashrrev_i32_e32 v87, 31, v86
	v_lshlrev_b64 v[84:85], 13, v[86:87]
	v_lshl_add_u64 v[84:85], v[10:11], 0, v[84:85]
	global_load_dwordx4 v[72:75], v[84:85], off
	s_or_b64 exec, exec, s[4:5]
	v_add_u32_e32 v83, 48, v12
	v_cmp_gt_i32_e64 s[4:5], s13, v83
	s_and_b64 s[16:17], s[4:5], vcc
	v_mov_b32_e32 v76, 0
	v_mov_b32_e32 v77, 0
	v_mov_b32_e32 v78, 0
	v_mov_b32_e32 v79, 0
	s_and_saveexec_b64 s[4:5], s[16:17]
	v_mov_b32_e32 v86, v83
	v_ashrrev_i32_e32 v87, 31, v86
	v_lshlrev_b64 v[84:85], 13, v[86:87]
	v_lshl_add_u64 v[84:85], v[10:11], 0, v[84:85]
	global_load_dwordx4 v[76:79], v[84:85], off
	s_or_b64 exec, exec, s[4:5]
	s_waitcnt vmcnt(0)
	ds_write2_b32 v20, v64, v65 offset1:1
	ds_write2_b32 v20, v66, v67 offset0:2 offset1:3
	ds_write2_b32 v21, v68, v69 offset1:1
	ds_write2_b32 v22, v70, v71 offset1:1
	ds_write2_b32 v23, v72, v73 offset1:1
	ds_write2_b32 v24, v74, v75 offset1:1
	ds_write2_b32 v25, v76, v77 offset1:1
	ds_write2_b32 v26, v78, v79 offset1:1
	s_branch .LBB0_39

.LBB0_50:
	s_or_b64 exec, exec, s[4:5]
	s_waitcnt vmcnt(0)
	s_waitcnt lgkmcnt(0)
	s_barrier
	ds_read2_b32 v[4:5], v19 offset1:32
	ds_read2_b32 v[10:11], v19 offset0:65 offset1:97
	ds_read2_b32 v[12:13], v19 offset0:130 offset1:162
	ds_read2_b32 v[14:15], v19 offset0:195 offset1:227
	ds_read2_b32 v[28:29], v27 offset0:4 offset1:36
	ds_read2_b32 v[30:31], v27 offset0:69 offset1:101
	ds_read2_b32 v[32:33], v27 offset0:134 offset1:166
	ds_read2_b32 v[34:35], v27 offset0:199 offset1:231
	s_sub_i32 s4, 0, s17
	s_add_i32 s4, s13, s4
	v_add_u32_e32 v38, s8, v18
	s_ashr_i32 s5, s4, 31
	v_ashrrev_i32_e32 v39, 31, v38
	v_lshl_add_u64 v[36:37], s[4:5], 1, v[8:9]
	v_lshlrev_b64 v[40:41], 12, v[38:39]
	s_waitcnt lgkmcnt(6)
	v_cvt_pk_bf16_f32 v0, v4, v10
	s_waitcnt lgkmcnt(4)
	v_cvt_pk_bf16_f32 v1, v12, v14
	s_waitcnt lgkmcnt(2)
	v_cvt_pk_bf16_f32 v2, v28, v30
	s_waitcnt lgkmcnt(0)
	v_cvt_pk_bf16_f32 v3, v32, v34
	v_lshl_add_u64 v[40:41], v[36:37], 0, v[40:41]
	v_add_u32_e32 v4, 32, v38
	global_store_dwordx4 v[40:41], v[0:3], off
	s_add_i32 s12, s12, s3
	s_add_i32 s13, s13, s14
	v_cvt_pk_bf16_f32 v0, v5, v11
	v_ashrrev_i32_e32 v5, 31, v4
	v_lshlrev_b64 v[4:5], 12, v[4:5]
	v_cvt_pk_bf16_f32 v1, v13, v15
	v_cvt_pk_bf16_f32 v2, v29, v31
	v_cvt_pk_bf16_f32 v3, v33, v35
	v_lshl_add_u64 v[4:5], v[36:37], 0, v[4:5]
	s_cmpk_lt_i32 s12, 0x1000
	global_store_dwordx4 v[4:5], v[0:3], off
	s_cbranch_scc0 .LBB0_59
.LBB0_51:
	s_ashr_i32 s4, s12, 31
	s_lshr_b32 s4, s4, 27
	s_add_i32 s4, s12, s4
	s_ashr_i32 s4, s4, 5
	s_lshl_b32 s17, s4, 11
	s_lshl_b32 s8, s4, 6
	s_sub_i32 s4, s13, s17
	v_or_b32_e32 v0, s8, v17
	v_add_u32_e32 v12, s4, v16
	v_cmp_gt_i32_e32 vcc, s15, v0
	s_ashr_i32 s9, s8, 31
	v_cmp_gt_i32_e64 s[4:5], s16, v12
	v_lshl_add_u64 v[10:11], s[8:9], 2, v[6:7]
	s_and_b64 s[18:19], s[4:5], vcc
	v_mov_b32_e32 v0, 0
	v_mov_b32_e32 v1, 0
	v_mov_b32_e32 v2, 0
	v_mov_b32_e32 v3, 0
	s_barrier
	v_mov_b32_e32 v64, 0
	v_mov_b32_e32 v65, 0
	v_mov_b32_e32 v66, 0
	v_mov_b32_e32 v67, 0
	s_and_saveexec_b64 s[4:5], s[18:19]
	v_mov_b32_e32 v86, v12
	v_ashrrev_i32_e32 v87, 31, v86
	v_lshlrev_b64 v[84:85], 15, v[86:87]
	v_lshl_add_u64 v[84:85], v[10:11], 0, v[84:85]
	global_load_dwordx4 v[64:67], v[84:85], off
	s_or_b64 exec, exec, s[4:5]
	v_add_u32_e32 v81, 16, v12
	v_cmp_gt_i32_e64 s[4:5], s16, v81
	s_and_b64 s[18:19], s[4:5], vcc
	v_mov_b32_e32 v68, 0
	v_mov_b32_e32 v69, 0
	v_mov_b32_e32 v70, 0
	v_mov_b32_e32 v71, 0
	s_and_saveexec_b64 s[4:5], s[18:19]
	v_mov_b32_e32 v86, v81
	v_ashrrev_i32_e32 v87, 31, v86
	v_lshlrev_b64 v[84:85], 15, v[86:87]
	v_lshl_add_u64 v[84:85], v[10:11], 0, v[84:85]
	global_load_dwordx4 v[68:71], v[84:85], off
	s_or_b64 exec, exec, s[4:5]
	v_add_u32_e32 v82, 32, v12
	v_cmp_gt_i32_e64 s[4:5], s16, v82
	s_and_b64 s[18:19], s[4:5], vcc
	v_mov_b32_e32 v72, 0
	v_mov_b32_e32 v73, 0
	v_mov_b32_e32 v74, 0
	v_mov_b32_e32 v75, 0
	s_and_saveexec_b64 s[4:5], s[18:19]
	v_mov_b32_e32 v86, v82
	v_ashrrev_i32_e32 v87, 31, v86
	v_lshlrev_b64 v[84:85], 15, v[86:87]
	v_lshl_add_u64 v[84:85], v[10:11], 0, v[84:85]
	global_load_dwordx4 v[72:75], v[84:85], off
	s_or_b64 exec, exec, s[4:5]
	v_add_u32_e32 v83, 48, v12
	v_cmp_gt_i32_e64 s[4:5], s16, v83
	s_and_b64 s[18:19], s[4:5], vcc
	v_mov_b32_e32 v76, 0
	v_mov_b32_e32 v77, 0
	v_mov_b32_e32 v78, 0
	v_mov_b32_e32 v79, 0
	s_and_saveexec_b64 s[4:5], s[18:19]
	v_mov_b32_e32 v86, v83
	v_ashrrev_i32_e32 v87, 31, v86
	v_lshlrev_b64 v[84:85], 15, v[86:87]
	v_lshl_add_u64 v[84:85], v[10:11], 0, v[84:85]
	global_load_dwordx4 v[76:79], v[84:85], off
	s_or_b64 exec, exec, s[4:5]
	s_waitcnt vmcnt(0)
	ds_write2_b32 v20, v64, v65 offset1:1
	ds_write2_b32 v20, v66, v67 offset0:2 offset1:3
	ds_write2_b32 v21, v68, v69 offset1:1
	ds_write2_b32 v22, v70, v71 offset1:1
	ds_write2_b32 v23, v72, v73 offset1:1
	ds_write2_b32 v24, v74, v75 offset1:1
	ds_write2_b32 v25, v76, v77 offset1:1
	ds_write2_b32 v26, v78, v79 offset1:1
	s_branch .LBB0_50

.LBB0_62:
	s_or_b64 exec, exec, s[4:5]
	s_waitcnt vmcnt(0)
	s_waitcnt lgkmcnt(0)
	s_barrier
	ds_read2_b32 v[4:5], v19 offset1:32
	ds_read2_b32 v[10:11], v19 offset0:65 offset1:97
	ds_read2_b32 v[12:13], v19 offset0:130 offset1:162
	ds_read2_b32 v[14:15], v19 offset0:195 offset1:227
	ds_read2_b32 v[28:29], v27 offset0:4 offset1:36
	ds_read2_b32 v[30:31], v27 offset0:69 offset1:101
	ds_read2_b32 v[32:33], v27 offset0:134 offset1:166
	ds_read2_b32 v[34:35], v27 offset0:199 offset1:231
	s_sub_i32 s4, 0, s17
	s_add_i32 s4, s13, s4
	v_add_u32_e32 v38, s10, v18
	s_ashr_i32 s5, s4, 31
	v_ashrrev_i32_e32 v39, 31, v38
	v_lshl_add_u64 v[36:37], s[4:5], 1, v[8:9]
	v_lshlrev_b64 v[40:41], 12, v[38:39]
	s_waitcnt lgkmcnt(6)
	v_cvt_pk_bf16_f32 v0, v4, v10
	s_waitcnt lgkmcnt(4)
	v_cvt_pk_bf16_f32 v1, v12, v14
	s_waitcnt lgkmcnt(2)
	v_cvt_pk_bf16_f32 v2, v28, v30
	s_waitcnt lgkmcnt(0)
	v_cvt_pk_bf16_f32 v3, v32, v34
	v_lshl_add_u64 v[40:41], v[36:37], 0, v[40:41]
	v_add_u32_e32 v4, 32, v38
	global_store_dwordx4 v[40:41], v[0:3], off
	s_add_i32 s12, s12, s3
	s_add_i32 s13, s13, s14
	v_cvt_pk_bf16_f32 v0, v5, v11
	v_ashrrev_i32_e32 v5, 31, v4
	v_lshlrev_b64 v[4:5], 12, v[4:5]
	v_cvt_pk_bf16_f32 v1, v13, v15
	v_cvt_pk_bf16_f32 v2, v29, v31
	v_cvt_pk_bf16_f32 v3, v33, v35
	v_lshl_add_u64 v[4:5], v[36:37], 0, v[4:5]
	s_cmpk_lt_i32 s12, 0x1000
	global_store_dwordx4 v[4:5], v[0:3], off
	s_cbranch_scc0 .LBB0_71
.LBB0_63:
	s_ashr_i32 s4, s12, 31
	s_lshr_b32 s4, s4, 27
	s_add_i32 s4, s12, s4
	s_ashr_i32 s4, s4, 5
	s_lshl_b32 s17, s4, 11
	s_lshl_b32 s10, s4, 6
	s_sub_i32 s4, s13, s17
	v_or_b32_e32 v0, s10, v17
	v_add_u32_e32 v12, s4, v16
	v_cmp_gt_i32_e32 vcc, s15, v0
	s_ashr_i32 s11, s10, 31
	v_cmp_gt_i32_e64 s[4:5], s16, v12
	v_lshl_add_u64 v[10:11], s[10:11], 2, v[6:7]
	s_and_b64 s[18:19], s[4:5], vcc
	v_mov_b32_e32 v0, 0
	v_mov_b32_e32 v1, 0
	v_mov_b32_e32 v2, 0
	v_mov_b32_e32 v3, 0
	s_barrier
	v_mov_b32_e32 v64, 0
	v_mov_b32_e32 v65, 0
	v_mov_b32_e32 v66, 0
	v_mov_b32_e32 v67, 0
	s_and_saveexec_b64 s[4:5], s[18:19]
	v_mov_b32_e32 v86, v12
	v_ashrrev_i32_e32 v87, 31, v86
	v_lshlrev_b64 v[84:85], 15, v[86:87]
	v_lshl_add_u64 v[84:85], v[10:11], 0, v[84:85]
	global_load_dwordx4 v[64:67], v[84:85], off
	s_or_b64 exec, exec, s[4:5]
	v_add_u32_e32 v81, 16, v12
	v_cmp_gt_i32_e64 s[4:5], s16, v81
	s_and_b64 s[18:19], s[4:5], vcc
	v_mov_b32_e32 v68, 0
	v_mov_b32_e32 v69, 0
	v_mov_b32_e32 v70, 0
	v_mov_b32_e32 v71, 0
	s_and_saveexec_b64 s[4:5], s[18:19]
	v_mov_b32_e32 v86, v81
	v_ashrrev_i32_e32 v87, 31, v86
	v_lshlrev_b64 v[84:85], 15, v[86:87]
	v_lshl_add_u64 v[84:85], v[10:11], 0, v[84:85]
	global_load_dwordx4 v[68:71], v[84:85], off
	s_or_b64 exec, exec, s[4:5]
	v_add_u32_e32 v82, 32, v12
	v_cmp_gt_i32_e64 s[4:5], s16, v82
	s_and_b64 s[18:19], s[4:5], vcc
	v_mov_b32_e32 v72, 0
	v_mov_b32_e32 v73, 0
	v_mov_b32_e32 v74, 0
	v_mov_b32_e32 v75, 0
	s_and_saveexec_b64 s[4:5], s[18:19]
	v_mov_b32_e32 v86, v82
	v_ashrrev_i32_e32 v87, 31, v86
	v_lshlrev_b64 v[84:85], 15, v[86:87]
	v_lshl_add_u64 v[84:85], v[10:11], 0, v[84:85]
	global_load_dwordx4 v[72:75], v[84:85], off
	s_or_b64 exec, exec, s[4:5]
	v_add_u32_e32 v83, 48, v12
	v_cmp_gt_i32_e64 s[4:5], s16, v83
	s_and_b64 s[18:19], s[4:5], vcc
	v_mov_b32_e32 v76, 0
	v_mov_b32_e32 v77, 0
	v_mov_b32_e32 v78, 0
	v_mov_b32_e32 v79, 0
	s_and_saveexec_b64 s[4:5], s[18:19]
	v_mov_b32_e32 v86, v83
	v_ashrrev_i32_e32 v87, 31, v86
	v_lshlrev_b64 v[84:85], 15, v[86:87]
	v_lshl_add_u64 v[84:85], v[10:11], 0, v[84:85]
	global_load_dwordx4 v[76:79], v[84:85], off
	s_or_b64 exec, exec, s[4:5]
	s_waitcnt vmcnt(0)
	ds_write2_b32 v20, v64, v65 offset1:1
	ds_write2_b32 v20, v66, v67 offset0:2 offset1:3
	ds_write2_b32 v21, v68, v69 offset1:1
	ds_write2_b32 v22, v70, v71 offset1:1
	ds_write2_b32 v23, v72, v73 offset1:1
	ds_write2_b32 v24, v74, v75 offset1:1
	ds_write2_b32 v25, v76, v77 offset1:1
	ds_write2_b32 v26, v78, v79 offset1:1
	s_branch .LBB0_62

.LBB0_73:
	s_or_b64 exec, exec, s[4:5]
	s_waitcnt vmcnt(0)
	s_waitcnt lgkmcnt(0)
	s_barrier
	ds_read2_b32 v[4:5], v19 offset1:32
	ds_read2_b32 v[10:11], v19 offset0:65 offset1:97
	ds_read2_b32 v[12:13], v19 offset0:130 offset1:162
	ds_read2_b32 v[14:15], v19 offset0:195 offset1:227
	ds_read2_b32 v[28:29], v27 offset0:4 offset1:36
	ds_read2_b32 v[30:31], v27 offset0:69 offset1:101
	ds_read2_b32 v[32:33], v27 offset0:134 offset1:166
	ds_read2_b32 v[34:35], v27 offset0:199 offset1:231
	s_sub_i32 s4, 0, s19
	s_add_i32 s4, s15, s4
	v_add_u32_e32 v38, s12, v18
	s_ashr_i32 s5, s4, 31
	v_ashrrev_i32_e32 v39, 31, v38
	v_lshl_add_u64 v[36:37], s[4:5], 1, v[8:9]
	v_lshlrev_b64 v[40:41], 14, v[38:39]
	s_waitcnt lgkmcnt(6)
	v_cvt_pk_bf16_f32 v0, v4, v10
	s_waitcnt lgkmcnt(4)
	v_cvt_pk_bf16_f32 v1, v12, v14
	s_waitcnt lgkmcnt(2)
	v_cvt_pk_bf16_f32 v2, v28, v30
	s_waitcnt lgkmcnt(0)
	v_cvt_pk_bf16_f32 v3, v32, v34
	v_lshl_add_u64 v[40:41], v[36:37], 0, v[40:41]
	v_add_u32_e32 v4, 32, v38
	global_store_dwordx4 v[40:41], v[0:3], off
	s_add_i32 s14, s14, s3
	s_add_i32 s15, s15, s16
	v_cvt_pk_bf16_f32 v0, v5, v11
	v_ashrrev_i32_e32 v5, 31, v4
	v_lshlrev_b64 v[4:5], 14, v[4:5]
	v_cvt_pk_bf16_f32 v1, v13, v15
	v_cvt_pk_bf16_f32 v2, v29, v31
	v_cvt_pk_bf16_f32 v3, v33, v35
	v_lshl_add_u64 v[4:5], v[36:37], 0, v[4:5]
	s_cmpk_lt_i32 s14, 0x1000
	global_store_dwordx4 v[4:5], v[0:3], off
	s_cbranch_scc0 .LBB0_82
.LBB0_74:
	s_ashr_i32 s4, s14, 31
	s_lshr_b32 s4, s4, 25
	s_add_i32 s4, s14, s4
	s_ashr_i32 s4, s4, 7
	s_lshl_b32 s19, s4, 13
	s_lshl_b32 s12, s4, 6
	s_sub_i32 s4, s15, s19
	v_or_b32_e32 v0, s12, v17
	v_add_u32_e32 v12, s4, v16
	v_cmp_gt_i32_e32 vcc, s17, v0
	s_ashr_i32 s13, s12, 31
	v_cmp_gt_i32_e64 s[4:5], s18, v12
	v_lshl_add_u64 v[10:11], s[12:13], 2, v[6:7]
	s_and_b64 s[20:21], s[4:5], vcc
	v_mov_b32_e32 v0, 0
	v_mov_b32_e32 v1, 0
	v_mov_b32_e32 v2, 0
	v_mov_b32_e32 v3, 0
	s_barrier
	v_mov_b32_e32 v64, 0
	v_mov_b32_e32 v65, 0
	v_mov_b32_e32 v66, 0
	v_mov_b32_e32 v67, 0
	s_and_saveexec_b64 s[4:5], s[20:21]
	v_mov_b32_e32 v86, v12
	v_ashrrev_i32_e32 v87, 31, v86
	v_lshlrev_b64 v[84:85], 13, v[86:87]
	v_lshl_add_u64 v[84:85], v[10:11], 0, v[84:85]
	global_load_dwordx4 v[64:67], v[84:85], off
	s_or_b64 exec, exec, s[4:5]
	v_add_u32_e32 v81, 16, v12
	v_cmp_gt_i32_e64 s[4:5], s18, v81
	s_and_b64 s[20:21], s[4:5], vcc
	v_mov_b32_e32 v68, 0
	v_mov_b32_e32 v69, 0
	v_mov_b32_e32 v70, 0
	v_mov_b32_e32 v71, 0
	s_and_saveexec_b64 s[4:5], s[20:21]
	v_mov_b32_e32 v86, v81
	v_ashrrev_i32_e32 v87, 31, v86
	v_lshlrev_b64 v[84:85], 13, v[86:87]
	v_lshl_add_u64 v[84:85], v[10:11], 0, v[84:85]
	global_load_dwordx4 v[68:71], v[84:85], off
	s_or_b64 exec, exec, s[4:5]
	v_add_u32_e32 v82, 32, v12
	v_cmp_gt_i32_e64 s[4:5], s18, v82
	s_and_b64 s[20:21], s[4:5], vcc
	v_mov_b32_e32 v72, 0
	v_mov_b32_e32 v73, 0
	v_mov_b32_e32 v74, 0
	v_mov_b32_e32 v75, 0
	s_and_saveexec_b64 s[4:5], s[20:21]
	v_mov_b32_e32 v86, v82
	v_ashrrev_i32_e32 v87, 31, v86
	v_lshlrev_b64 v[84:85], 13, v[86:87]
	v_lshl_add_u64 v[84:85], v[10:11], 0, v[84:85]
	global_load_dwordx4 v[72:75], v[84:85], off
	s_or_b64 exec, exec, s[4:5]
	v_add_u32_e32 v83, 48, v12
	v_cmp_gt_i32_e64 s[4:5], s18, v83
	s_and_b64 s[20:21], s[4:5], vcc
	v_mov_b32_e32 v76, 0
	v_mov_b32_e32 v77, 0
	v_mov_b32_e32 v78, 0
	v_mov_b32_e32 v79, 0
	s_and_saveexec_b64 s[4:5], s[20:21]
	v_mov_b32_e32 v86, v83
	v_ashrrev_i32_e32 v87, 31, v86
	v_lshlrev_b64 v[84:85], 13, v[86:87]
	v_lshl_add_u64 v[84:85], v[10:11], 0, v[84:85]
	global_load_dwordx4 v[76:79], v[84:85], off
	s_or_b64 exec, exec, s[4:5]
	s_waitcnt vmcnt(0)
	ds_write2_b32 v20, v64, v65 offset1:1
	ds_write2_b32 v20, v66, v67 offset0:2 offset1:3
	ds_write2_b32 v21, v68, v69 offset1:1
	ds_write2_b32 v22, v70, v71 offset1:1
	ds_write2_b32 v23, v72, v73 offset1:1
	ds_write2_b32 v24, v74, v75 offset1:1
	ds_write2_b32 v25, v76, v77 offset1:1
	ds_write2_b32 v26, v78, v79 offset1:1
	s_branch .LBB0_73

.LBB0_85:
	s_or_b64 exec, exec, s[4:5]
	s_waitcnt vmcnt(0)
	s_waitcnt lgkmcnt(0)
	s_barrier
	ds_read2_b32 v[4:5], v19 offset1:32
	ds_read2_b32 v[10:11], v19 offset0:65 offset1:97
	ds_read2_b32 v[12:13], v19 offset0:130 offset1:162
	ds_read2_b32 v[14:15], v19 offset0:195 offset1:227
	ds_read2_b32 v[28:29], v27 offset0:4 offset1:36
	ds_read2_b32 v[30:31], v27 offset0:69 offset1:101
	ds_read2_b32 v[32:33], v27 offset0:134 offset1:166
	ds_read2_b32 v[34:35], v27 offset0:199 offset1:231
	s_sub_i32 s4, 0, s15
	s_add_i32 s4, s10, s4
	v_add_u32_e32 v38, s8, v18
	s_ashr_i32 s5, s4, 31
	v_ashrrev_i32_e32 v39, 31, v38
	v_lshl_add_u64 v[36:37], s[4:5], 1, v[8:9]
	v_lshlrev_b64 v[40:41], 14, v[38:39]
	s_waitcnt lgkmcnt(6)
	v_cvt_pk_bf16_f32 v0, v4, v10
	s_waitcnt lgkmcnt(4)
	v_cvt_pk_bf16_f32 v1, v12, v14
	s_waitcnt lgkmcnt(2)
	v_cvt_pk_bf16_f32 v2, v28, v30
	s_waitcnt lgkmcnt(0)
	v_cvt_pk_bf16_f32 v3, v32, v34
	v_lshl_add_u64 v[40:41], v[36:37], 0, v[40:41]
	v_add_u32_e32 v4, 32, v38
	global_store_dwordx4 v[40:41], v[0:3], off
	s_add_i32 s12, s12, s3
	s_add_i32 s10, s10, s11
	v_cvt_pk_bf16_f32 v0, v5, v11
	v_ashrrev_i32_e32 v5, 31, v4
	v_lshlrev_b64 v[4:5], 14, v[4:5]
	v_cvt_pk_bf16_f32 v1, v13, v15
	v_cvt_pk_bf16_f32 v2, v29, v31
	v_cvt_pk_bf16_f32 v3, v33, v35
	v_lshl_add_u64 v[4:5], v[36:37], 0, v[4:5]
	s_cmpk_lt_i32 s12, 0x1000
	global_store_dwordx4 v[4:5], v[0:3], off
	s_cbranch_scc0 .LBB0_94
.LBB0_86:
	s_ashr_i32 s4, s12, 31
	s_lshr_b32 s4, s4, 25
	s_add_i32 s4, s12, s4
	s_ashr_i32 s4, s4, 7
	s_lshl_b32 s15, s4, 13
	s_lshl_b32 s8, s4, 6
	s_sub_i32 s4, s10, s15
	v_or_b32_e32 v0, s8, v17
	v_add_u32_e32 v12, s4, v16
	v_cmp_gt_i32_e32 vcc, s13, v0
	s_ashr_i32 s9, s8, 31
	v_cmp_gt_i32_e64 s[4:5], s14, v12
	v_lshl_add_u64 v[10:11], s[8:9], 2, v[6:7]
	s_and_b64 s[16:17], s[4:5], vcc
	v_mov_b32_e32 v0, 0
	v_mov_b32_e32 v1, 0
	v_mov_b32_e32 v2, 0
	v_mov_b32_e32 v3, 0
	s_barrier
	v_mov_b32_e32 v64, 0
	v_mov_b32_e32 v65, 0
	v_mov_b32_e32 v66, 0
	v_mov_b32_e32 v67, 0
	s_and_saveexec_b64 s[4:5], s[16:17]
	v_mov_b32_e32 v86, v12
	v_ashrrev_i32_e32 v87, 31, v86
	v_lshlrev_b64 v[84:85], 13, v[86:87]
	v_lshl_add_u64 v[84:85], v[10:11], 0, v[84:85]
	global_load_dwordx4 v[64:67], v[84:85], off
	s_or_b64 exec, exec, s[4:5]
	v_add_u32_e32 v81, 16, v12
	v_cmp_gt_i32_e64 s[4:5], s14, v81
	s_and_b64 s[16:17], s[4:5], vcc
	v_mov_b32_e32 v68, 0
	v_mov_b32_e32 v69, 0
	v_mov_b32_e32 v70, 0
	v_mov_b32_e32 v71, 0
	s_and_saveexec_b64 s[4:5], s[16:17]
	v_mov_b32_e32 v86, v81
	v_ashrrev_i32_e32 v87, 31, v86
	v_lshlrev_b64 v[84:85], 13, v[86:87]
	v_lshl_add_u64 v[84:85], v[10:11], 0, v[84:85]
	global_load_dwordx4 v[68:71], v[84:85], off
	s_or_b64 exec, exec, s[4:5]
	v_add_u32_e32 v82, 32, v12
	v_cmp_gt_i32_e64 s[4:5], s14, v82
	s_and_b64 s[16:17], s[4:5], vcc
	v_mov_b32_e32 v72, 0
	v_mov_b32_e32 v73, 0
	v_mov_b32_e32 v74, 0
	v_mov_b32_e32 v75, 0
	s_and_saveexec_b64 s[4:5], s[16:17]
	v_mov_b32_e32 v86, v82
	v_ashrrev_i32_e32 v87, 31, v86
	v_lshlrev_b64 v[84:85], 13, v[86:87]
	v_lshl_add_u64 v[84:85], v[10:11], 0, v[84:85]
	global_load_dwordx4 v[72:75], v[84:85], off
	s_or_b64 exec, exec, s[4:5]
	v_add_u32_e32 v83, 48, v12
	v_cmp_gt_i32_e64 s[4:5], s14, v83
	s_and_b64 s[16:17], s[4:5], vcc
	v_mov_b32_e32 v76, 0
	v_mov_b32_e32 v77, 0
	v_mov_b32_e32 v78, 0
	v_mov_b32_e32 v79, 0
	s_and_saveexec_b64 s[4:5], s[16:17]
	v_mov_b32_e32 v86, v83
	v_ashrrev_i32_e32 v87, 31, v86
	v_lshlrev_b64 v[84:85], 13, v[86:87]
	v_lshl_add_u64 v[84:85], v[10:11], 0, v[84:85]
	global_load_dwordx4 v[76:79], v[84:85], off
	s_or_b64 exec, exec, s[4:5]
	s_waitcnt vmcnt(0)
	ds_write2_b32 v20, v64, v65 offset1:1
	ds_write2_b32 v20, v66, v67 offset0:2 offset1:3
	ds_write2_b32 v21, v68, v69 offset1:1
	ds_write2_b32 v22, v70, v71 offset1:1
	ds_write2_b32 v23, v72, v73 offset1:1
	ds_write2_b32 v24, v74, v75 offset1:1
	ds_write2_b32 v25, v76, v77 offset1:1
	ds_write2_b32 v26, v78, v79 offset1:1
	s_branch .LBB0_85

.LBB0_140:
	s_or_b64 exec, exec, s[4:5]
	s_waitcnt vmcnt(0)
	s_waitcnt lgkmcnt(0)
	s_barrier
	ds_read2_b32 v[4:5], v15 offset1:32
	ds_read2_b32 v[10:11], v15 offset0:65 offset1:97
	ds_read2_b32 v[24:25], v15 offset0:130 offset1:162
	ds_read2_b32 v[26:27], v15 offset0:195 offset1:227
	ds_read2_b32 v[28:29], v23 offset0:4 offset1:36
	ds_read2_b32 v[30:31], v23 offset0:69 offset1:101
	ds_read2_b32 v[32:33], v23 offset0:134 offset1:166
	ds_read2_b32 v[34:35], v23 offset0:199 offset1:231
	s_sub_i32 s4, 0, s16
	s_add_i32 s4, s11, s4
	v_add_u32_e32 v38, s8, v14
	s_ashr_i32 s5, s4, 31
	v_ashrrev_i32_e32 v39, 31, v38
	v_lshl_add_u64 v[36:37], s[4:5], 1, v[8:9]
	v_lshlrev_b64 v[40:41], 12, v[38:39]
	s_waitcnt lgkmcnt(6)
	v_cvt_pk_bf16_f32 v0, v4, v10
	s_waitcnt lgkmcnt(4)
	v_cvt_pk_bf16_f32 v1, v24, v26
	s_waitcnt lgkmcnt(2)
	v_cvt_pk_bf16_f32 v2, v28, v30
	s_waitcnt lgkmcnt(0)
	v_cvt_pk_bf16_f32 v3, v32, v34
	v_lshl_add_u64 v[40:41], v[36:37], 0, v[40:41]
	v_add_u32_e32 v4, 32, v38
	global_store_dwordx4 v[40:41], v[0:3], off
	s_add_i32 s10, s10, s3
	s_add_i32 s11, s11, s12
	v_cvt_pk_bf16_f32 v0, v5, v11
	v_ashrrev_i32_e32 v5, 31, v4
	v_lshlrev_b64 v[4:5], 12, v[4:5]
	v_cvt_pk_bf16_f32 v1, v25, v27
	v_cvt_pk_bf16_f32 v2, v29, v31
	v_cvt_pk_bf16_f32 v3, v33, v35
	v_lshl_add_u64 v[4:5], v[36:37], 0, v[4:5]
	s_cmp_lt_i32 s10, 64
	global_store_dwordx4 v[4:5], v[0:3], off
	s_cbranch_scc0 .LBB0_149
.LBB0_141:
	s_ashr_i32 s4, s10, 31
	s_lshr_b32 s4, s4, 27
	s_add_i32 s4, s10, s4
	s_ashr_i32 s4, s4, 5
	s_lshl_b32 s16, s4, 11
	s_lshl_b32 s8, s4, 6
	s_sub_i32 s4, s11, s16
	v_or_b32_e32 v0, s8, v13
	v_add_u32_e32 v24, s4, v12
	v_cmp_gt_i32_e32 vcc, s13, v0
	s_ashr_i32 s9, s8, 31
	v_cmp_gt_i32_e64 s[4:5], s14, v24
	v_lshl_add_u64 v[10:11], s[8:9], 2, v[6:7]
	s_and_b64 s[18:19], s[4:5], vcc
	v_mov_b32_e32 v0, 0
	v_mov_b32_e32 v1, 0
	v_mov_b32_e32 v2, 0
	v_mov_b32_e32 v3, 0
	s_barrier
	v_mov_b32_e32 v64, 0
	v_mov_b32_e32 v65, 0
	v_mov_b32_e32 v66, 0
	v_mov_b32_e32 v67, 0
	s_and_saveexec_b64 s[4:5], s[18:19]
	v_mad_i64_i32 v[84:85], s[18:19], v24, s15, v[10:11]
	global_load_dwordx4 v[64:67], v[84:85], off
	s_or_b64 exec, exec, s[4:5]
	v_add_u32_e32 v81, 16, v24
	v_cmp_gt_i32_e64 s[4:5], s14, v81
	s_and_b64 s[18:19], s[4:5], vcc
	v_mov_b32_e32 v68, 0
	v_mov_b32_e32 v69, 0
	v_mov_b32_e32 v70, 0
	v_mov_b32_e32 v71, 0
	s_and_saveexec_b64 s[4:5], s[18:19]
	v_mad_i64_i32 v[84:85], s[18:19], v81, s15, v[10:11]
	global_load_dwordx4 v[68:71], v[84:85], off
	s_or_b64 exec, exec, s[4:5]
	v_add_u32_e32 v82, 32, v24
	v_cmp_gt_i32_e64 s[4:5], s14, v82
	s_and_b64 s[18:19], s[4:5], vcc
	v_mov_b32_e32 v72, 0
	v_mov_b32_e32 v73, 0
	v_mov_b32_e32 v74, 0
	v_mov_b32_e32 v75, 0
	s_and_saveexec_b64 s[4:5], s[18:19]
	v_mad_i64_i32 v[84:85], s[18:19], v82, s15, v[10:11]
	global_load_dwordx4 v[72:75], v[84:85], off
	s_or_b64 exec, exec, s[4:5]
	v_add_u32_e32 v83, 48, v24
	v_cmp_gt_i32_e64 s[4:5], s14, v83
	s_and_b64 s[18:19], s[4:5], vcc
	v_mov_b32_e32 v76, 0
	v_mov_b32_e32 v77, 0
	v_mov_b32_e32 v78, 0
	v_mov_b32_e32 v79, 0
	s_and_saveexec_b64 s[4:5], s[18:19]
	v_mad_i64_i32 v[84:85], s[18:19], v83, s15, v[10:11]
	global_load_dwordx4 v[76:79], v[84:85], off
	s_or_b64 exec, exec, s[4:5]
	s_waitcnt vmcnt(0)
	ds_write2_b32 v16, v64, v65 offset1:1
	ds_write2_b32 v16, v66, v67 offset0:2 offset1:3
	ds_write2_b32 v17, v68, v69 offset1:1
	ds_write2_b32 v18, v70, v71 offset1:1
	ds_write2_b32 v19, v72, v73 offset1:1
	ds_write2_b32 v20, v74, v75 offset1:1
	ds_write2_b32 v21, v76, v77 offset1:1
	ds_write2_b32 v22, v78, v79 offset1:1
	s_branch .LBB0_140

.LBB0_162:
	s_or_b64 exec, exec, s[4:5]
	s_waitcnt vmcnt(0)
	s_waitcnt lgkmcnt(0)
	s_barrier
	ds_read2_b32 v[4:5], v19 offset1:32
	ds_read2_b32 v[10:11], v19 offset0:65 offset1:97
	ds_read2_b32 v[12:13], v19 offset0:130 offset1:162
	ds_read2_b32 v[14:15], v19 offset0:195 offset1:227
	ds_read2_b32 v[28:29], v27 offset0:4 offset1:36
	ds_read2_b32 v[30:31], v27 offset0:69 offset1:101
	ds_read2_b32 v[32:33], v27 offset0:134 offset1:166
	ds_read2_b32 v[34:35], v27 offset0:199 offset1:231
	s_sub_i32 s4, 0, s15
	s_add_i32 s4, s11, s4
	v_add_u32_e32 v38, s8, v18
	s_ashr_i32 s5, s4, 31
	v_ashrrev_i32_e32 v39, 31, v38
	v_lshl_add_u64 v[36:37], s[4:5], 1, v[8:9]
	v_lshlrev_b64 v[40:41], 12, v[38:39]
	s_waitcnt lgkmcnt(6)
	v_cvt_pk_bf16_f32 v0, v4, v10
	s_waitcnt lgkmcnt(4)
	v_cvt_pk_bf16_f32 v1, v12, v14
	s_waitcnt lgkmcnt(2)
	v_cvt_pk_bf16_f32 v2, v28, v30
	s_waitcnt lgkmcnt(0)
	v_cvt_pk_bf16_f32 v3, v32, v34
	v_lshl_add_u64 v[40:41], v[36:37], 0, v[40:41]
	v_add_u32_e32 v4, 32, v38
	global_store_dwordx4 v[40:41], v[0:3], off
	s_add_i32 s10, s10, s3
	s_add_i32 s11, s11, s12
	v_cvt_pk_bf16_f32 v0, v5, v11
	v_ashrrev_i32_e32 v5, 31, v4
	v_lshlrev_b64 v[4:5], 12, v[4:5]
	v_cvt_pk_bf16_f32 v1, v13, v15
	v_cvt_pk_bf16_f32 v2, v29, v31
	v_cvt_pk_bf16_f32 v3, v33, v35
	v_lshl_add_u64 v[4:5], v[36:37], 0, v[4:5]
	s_cmpk_lt_i32 s10, 0x80
	global_store_dwordx4 v[4:5], v[0:3], off
	s_cbranch_scc0 .LBB0_171
.LBB0_163:
	s_ashr_i32 s4, s10, 31
	s_lshr_b32 s4, s4, 27
	s_add_i32 s4, s10, s4
	s_ashr_i32 s4, s4, 5
	s_lshl_b32 s15, s4, 11
	s_lshl_b32 s8, s4, 6
	s_sub_i32 s4, s11, s15
	v_or_b32_e32 v0, s8, v17
	v_add_u32_e32 v12, s4, v16
	v_cmp_gt_i32_e32 vcc, s13, v0
	s_ashr_i32 s9, s8, 31
	v_cmp_gt_i32_e64 s[4:5], s14, v12
	v_lshl_add_u64 v[10:11], s[8:9], 2, v[6:7]
	s_and_b64 s[16:17], s[4:5], vcc
	v_mov_b32_e32 v0, 0
	v_mov_b32_e32 v1, 0
	v_mov_b32_e32 v2, 0
	v_mov_b32_e32 v3, 0
	s_barrier
	v_mov_b32_e32 v64, 0
	v_mov_b32_e32 v65, 0
	v_mov_b32_e32 v66, 0
	v_mov_b32_e32 v67, 0
	s_and_saveexec_b64 s[4:5], s[16:17]
	v_mov_b32_e32 v86, v12
	v_ashrrev_i32_e32 v87, 31, v86
	v_lshlrev_b64 v[84:85], 10, v[86:87]
	v_lshl_add_u64 v[84:85], v[10:11], 0, v[84:85]
	global_load_dwordx4 v[64:67], v[84:85], off
	s_or_b64 exec, exec, s[4:5]
	v_add_u32_e32 v81, 16, v12
	v_cmp_gt_i32_e64 s[4:5], s14, v81
	s_and_b64 s[16:17], s[4:5], vcc
	v_mov_b32_e32 v68, 0
	v_mov_b32_e32 v69, 0
	v_mov_b32_e32 v70, 0
	v_mov_b32_e32 v71, 0
	s_and_saveexec_b64 s[4:5], s[16:17]
	v_mov_b32_e32 v86, v81
	v_ashrrev_i32_e32 v87, 31, v86
	v_lshlrev_b64 v[84:85], 10, v[86:87]
	v_lshl_add_u64 v[84:85], v[10:11], 0, v[84:85]
	global_load_dwordx4 v[68:71], v[84:85], off
	s_or_b64 exec, exec, s[4:5]
	v_add_u32_e32 v82, 32, v12
	v_cmp_gt_i32_e64 s[4:5], s14, v82
	s_and_b64 s[16:17], s[4:5], vcc
	v_mov_b32_e32 v72, 0
	v_mov_b32_e32 v73, 0
	v_mov_b32_e32 v74, 0
	v_mov_b32_e32 v75, 0
	s_and_saveexec_b64 s[4:5], s[16:17]
	v_mov_b32_e32 v86, v82
	v_ashrrev_i32_e32 v87, 31, v86
	v_lshlrev_b64 v[84:85], 10, v[86:87]
	v_lshl_add_u64 v[84:85], v[10:11], 0, v[84:85]
	global_load_dwordx4 v[72:75], v[84:85], off
	s_or_b64 exec, exec, s[4:5]
	v_add_u32_e32 v83, 48, v12
	v_cmp_gt_i32_e64 s[4:5], s14, v83
	s_and_b64 s[16:17], s[4:5], vcc
	v_mov_b32_e32 v76, 0
	v_mov_b32_e32 v77, 0
	v_mov_b32_e32 v78, 0
	v_mov_b32_e32 v79, 0
	s_and_saveexec_b64 s[4:5], s[16:17]
	v_mov_b32_e32 v86, v83
	v_ashrrev_i32_e32 v87, 31, v86
	v_lshlrev_b64 v[84:85], 10, v[86:87]
	v_lshl_add_u64 v[84:85], v[10:11], 0, v[84:85]
	global_load_dwordx4 v[76:79], v[84:85], off
	s_or_b64 exec, exec, s[4:5]
	s_waitcnt vmcnt(0)
	ds_write2_b32 v20, v64, v65 offset1:1
	ds_write2_b32 v20, v66, v67 offset0:2 offset1:3
	ds_write2_b32 v21, v68, v69 offset1:1
	ds_write2_b32 v22, v70, v71 offset1:1
	ds_write2_b32 v23, v72, v73 offset1:1
	ds_write2_b32 v24, v74, v75 offset1:1
	ds_write2_b32 v25, v76, v77 offset1:1
	ds_write2_b32 v26, v78, v79 offset1:1
	s_branch .LBB0_162

.LBB0_173:
	s_or_b64 exec, exec, s[4:5]
	s_waitcnt vmcnt(0)
	s_waitcnt lgkmcnt(0)
	s_barrier
	ds_read2_b32 v[4:5], v19 offset1:32
	ds_read2_b32 v[10:11], v19 offset0:65 offset1:97
	ds_read2_b32 v[12:13], v19 offset0:130 offset1:162
	ds_read2_b32 v[14:15], v19 offset0:195 offset1:227
	ds_read2_b32 v[28:29], v27 offset0:4 offset1:36
	ds_read2_b32 v[30:31], v27 offset0:69 offset1:101
	ds_read2_b32 v[32:33], v27 offset0:134 offset1:166
	ds_read2_b32 v[34:35], v27 offset0:199 offset1:231
	s_sub_i32 s4, 0, s15
	s_add_i32 s4, s11, s4
	v_add_u32_e32 v38, s8, v18
	s_ashr_i32 s5, s4, 31
	v_ashrrev_i32_e32 v39, 31, v38
	v_lshl_add_u64 v[36:37], s[4:5], 1, v[8:9]
	v_lshlrev_b64 v[40:41], 8, v[38:39]
	s_waitcnt lgkmcnt(6)
	v_cvt_pk_bf16_f32 v0, v4, v10
	s_waitcnt lgkmcnt(4)
	v_cvt_pk_bf16_f32 v1, v12, v14
	s_waitcnt lgkmcnt(2)
	v_cvt_pk_bf16_f32 v2, v28, v30
	s_waitcnt lgkmcnt(0)
	v_cvt_pk_bf16_f32 v3, v32, v34
	v_lshl_add_u64 v[40:41], v[36:37], 0, v[40:41]
	v_add_u32_e32 v4, 32, v38
	global_store_dwordx4 v[40:41], v[0:3], off
	s_add_i32 s10, s10, s3
	s_add_i32 s11, s11, s12
	v_cvt_pk_bf16_f32 v0, v5, v11
	v_ashrrev_i32_e32 v5, 31, v4
	v_lshlrev_b64 v[4:5], 8, v[4:5]
	v_cvt_pk_bf16_f32 v1, v13, v15
	v_cvt_pk_bf16_f32 v2, v29, v31
	v_cvt_pk_bf16_f32 v3, v33, v35
	v_lshl_add_u64 v[4:5], v[36:37], 0, v[4:5]
	s_cmp_lt_i32 s10, 64
	global_store_dwordx4 v[4:5], v[0:3], off
	s_cbranch_scc0 .LBB0_182
.LBB0_174:
	s_lshr_b32 s4, s10, 31
	s_add_i32 s4, s10, s4
	s_ashr_i32 s4, s4, 1
	s_lshl_b32 s15, s4, 7
	s_lshl_b32 s8, s4, 6
	s_sub_i32 s4, s11, s15
	v_or_b32_e32 v0, s8, v17
	v_add_u32_e32 v12, s4, v16
	v_cmp_gt_i32_e32 vcc, s13, v0
	s_ashr_i32 s9, s8, 31
	v_cmp_gt_i32_e64 s[4:5], s14, v12
	v_lshl_add_u64 v[10:11], s[8:9], 2, v[6:7]
	s_and_b64 s[16:17], s[4:5], vcc
	v_mov_b32_e32 v0, 0
	v_mov_b32_e32 v1, 0
	v_mov_b32_e32 v2, 0
	v_mov_b32_e32 v3, 0
	s_barrier
	v_mov_b32_e32 v64, 0
	v_mov_b32_e32 v65, 0
	v_mov_b32_e32 v66, 0
	v_mov_b32_e32 v67, 0
	s_and_saveexec_b64 s[4:5], s[16:17]
	v_mov_b32_e32 v86, v12
	v_ashrrev_i32_e32 v87, 31, v86
	v_lshlrev_b64 v[84:85], 13, v[86:87]
	v_lshl_add_u64 v[84:85], v[10:11], 0, v[84:85]
	global_load_dwordx4 v[64:67], v[84:85], off
	s_or_b64 exec, exec, s[4:5]
	v_add_u32_e32 v81, 16, v12
	v_cmp_gt_i32_e64 s[4:5], s14, v81
	s_and_b64 s[16:17], s[4:5], vcc
	v_mov_b32_e32 v68, 0
	v_mov_b32_e32 v69, 0
	v_mov_b32_e32 v70, 0
	v_mov_b32_e32 v71, 0
	s_and_saveexec_b64 s[4:5], s[16:17]
	v_mov_b32_e32 v86, v81
	v_ashrrev_i32_e32 v87, 31, v86
	v_lshlrev_b64 v[84:85], 13, v[86:87]
	v_lshl_add_u64 v[84:85], v[10:11], 0, v[84:85]
	global_load_dwordx4 v[68:71], v[84:85], off
	s_or_b64 exec, exec, s[4:5]
	v_add_u32_e32 v82, 32, v12
	v_cmp_gt_i32_e64 s[4:5], s14, v82
	s_and_b64 s[16:17], s[4:5], vcc
	v_mov_b32_e32 v72, 0
	v_mov_b32_e32 v73, 0
	v_mov_b32_e32 v74, 0
	v_mov_b32_e32 v75, 0
	s_and_saveexec_b64 s[4:5], s[16:17]
	v_mov_b32_e32 v86, v82
	v_ashrrev_i32_e32 v87, 31, v86
	v_lshlrev_b64 v[84:85], 13, v[86:87]
	v_lshl_add_u64 v[84:85], v[10:11], 0, v[84:85]
	global_load_dwordx4 v[72:75], v[84:85], off
	s_or_b64 exec, exec, s[4:5]
	v_add_u32_e32 v83, 48, v12
	v_cmp_gt_i32_e64 s[4:5], s14, v83
	s_and_b64 s[16:17], s[4:5], vcc
	v_mov_b32_e32 v76, 0
	v_mov_b32_e32 v77, 0
	v_mov_b32_e32 v78, 0
	v_mov_b32_e32 v79, 0
	s_and_saveexec_b64 s[4:5], s[16:17]
	v_mov_b32_e32 v86, v83
	v_ashrrev_i32_e32 v87, 31, v86
	v_lshlrev_b64 v[84:85], 13, v[86:87]
	v_lshl_add_u64 v[84:85], v[10:11], 0, v[84:85]
	global_load_dwordx4 v[76:79], v[84:85], off
	s_or_b64 exec, exec, s[4:5]
	s_waitcnt vmcnt(0)
	ds_write2_b32 v20, v64, v65 offset1:1
	ds_write2_b32 v20, v66, v67 offset0:2 offset1:3
	ds_write2_b32 v21, v68, v69 offset1:1
	ds_write2_b32 v22, v70, v71 offset1:1
	ds_write2_b32 v23, v72, v73 offset1:1
	ds_write2_b32 v24, v74, v75 offset1:1
	ds_write2_b32 v25, v76, v77 offset1:1
	ds_write2_b32 v26, v78, v79 offset1:1
	s_branch .LBB0_173

.LBB0_195:
	s_or_b64 exec, exec, s[4:5]
	s_waitcnt vmcnt(0)
	s_waitcnt lgkmcnt(0)
	s_barrier
	ds_read2_b32 v[4:5], v19 offset1:32
	ds_read2_b32 v[10:11], v19 offset0:65 offset1:97
	ds_read2_b32 v[12:13], v19 offset0:130 offset1:162
	ds_read2_b32 v[14:15], v19 offset0:195 offset1:227
	ds_read2_b32 v[28:29], v27 offset0:4 offset1:36
	ds_read2_b32 v[30:31], v27 offset0:69 offset1:101
	ds_read2_b32 v[32:33], v27 offset0:134 offset1:166
	ds_read2_b32 v[34:35], v27 offset0:199 offset1:231
	s_sub_i32 s1, 0, s11
	s_add_i32 s4, s6, s1
	v_add_u32_e32 v38, s0, v18
	s_ashr_i32 s5, s4, 31
	v_ashrrev_i32_e32 v39, 31, v38
	v_lshl_add_u64 v[36:37], s[4:5], 1, v[8:9]
	v_lshlrev_b64 v[40:41], 9, v[38:39]
	s_waitcnt lgkmcnt(6)
	v_cvt_pk_bf16_f32 v0, v4, v10
	s_waitcnt lgkmcnt(4)
	v_cvt_pk_bf16_f32 v1, v12, v14
	s_waitcnt lgkmcnt(2)
	v_cvt_pk_bf16_f32 v2, v28, v30
	s_waitcnt lgkmcnt(0)
	v_cvt_pk_bf16_f32 v3, v32, v34
	v_lshl_add_u64 v[40:41], v[36:37], 0, v[40:41]
	v_add_u32_e32 v4, 32, v38
	global_store_dwordx4 v[40:41], v[0:3], off
	s_add_i32 s8, s8, s3
	s_add_i32 s6, s6, s7
	v_cvt_pk_bf16_f32 v0, v5, v11
	v_ashrrev_i32_e32 v5, 31, v4
	v_lshlrev_b64 v[4:5], 9, v[4:5]
	v_cvt_pk_bf16_f32 v1, v13, v15
	v_cvt_pk_bf16_f32 v2, v29, v31
	v_cvt_pk_bf16_f32 v3, v33, v35
	v_lshl_add_u64 v[4:5], v[36:37], 0, v[4:5]
	s_cmpk_lt_i32 s8, 0x80
	global_store_dwordx4 v[4:5], v[0:3], off
	s_cbranch_scc0 .LBB0_204
.LBB0_196:
	s_ashr_i32 s0, s8, 31
	s_lshr_b32 s0, s0, 30
	s_add_i32 s0, s8, s0
	s_ashr_i32 s0, s0, 2
	s_lshl_b32 s11, s0, 8
	s_lshl_b32 s0, s0, 6
	s_ashr_i32 s1, s0, 31
	v_lshl_add_u64 v[10:11], s[0:1], 2, v[6:7]
	s_sub_i32 s1, s6, s11
	v_or_b32_e32 v0, s0, v17
	v_add_u32_e32 v12, s1, v16
	v_cmp_gt_i32_e32 vcc, s9, v0
	v_cmp_gt_i32_e64 s[4:5], s10, v12
	s_and_b64 s[12:13], s[4:5], vcc
	v_mov_b32_e32 v0, 0
	v_mov_b32_e32 v1, 0
	v_mov_b32_e32 v2, 0
	v_mov_b32_e32 v3, 0
	s_barrier
	v_mov_b32_e32 v64, 0
	v_mov_b32_e32 v65, 0
	v_mov_b32_e32 v66, 0
	v_mov_b32_e32 v67, 0
	s_and_saveexec_b64 s[4:5], s[12:13]
	v_mov_b32_e32 v86, v12
	v_ashrrev_i32_e32 v87, 31, v86
	v_lshlrev_b64 v[84:85], 13, v[86:87]
	v_lshl_add_u64 v[84:85], v[10:11], 0, v[84:85]
	global_load_dwordx4 v[64:67], v[84:85], off
	s_or_b64 exec, exec, s[4:5]
	v_add_u32_e32 v81, 16, v12
	v_cmp_gt_i32_e64 s[4:5], s10, v81
	s_and_b64 s[12:13], s[4:5], vcc
	v_mov_b32_e32 v68, 0
	v_mov_b32_e32 v69, 0
	v_mov_b32_e32 v70, 0
	v_mov_b32_e32 v71, 0
	s_and_saveexec_b64 s[4:5], s[12:13]
	v_mov_b32_e32 v86, v81
	v_ashrrev_i32_e32 v87, 31, v86
	v_lshlrev_b64 v[84:85], 13, v[86:87]
	v_lshl_add_u64 v[84:85], v[10:11], 0, v[84:85]
	global_load_dwordx4 v[68:71], v[84:85], off
	s_or_b64 exec, exec, s[4:5]
	v_add_u32_e32 v82, 32, v12
	v_cmp_gt_i32_e64 s[4:5], s10, v82
	s_and_b64 s[12:13], s[4:5], vcc
	v_mov_b32_e32 v72, 0
	v_mov_b32_e32 v73, 0
	v_mov_b32_e32 v74, 0
	v_mov_b32_e32 v75, 0
	s_and_saveexec_b64 s[4:5], s[12:13]
	v_mov_b32_e32 v86, v82
	v_ashrrev_i32_e32 v87, 31, v86
	v_lshlrev_b64 v[84:85], 13, v[86:87]
	v_lshl_add_u64 v[84:85], v[10:11], 0, v[84:85]
	global_load_dwordx4 v[72:75], v[84:85], off
	s_or_b64 exec, exec, s[4:5]
	v_add_u32_e32 v83, 48, v12
	v_cmp_gt_i32_e64 s[4:5], s10, v83
	s_and_b64 s[12:13], s[4:5], vcc
	v_mov_b32_e32 v76, 0
	v_mov_b32_e32 v77, 0
	v_mov_b32_e32 v78, 0
	v_mov_b32_e32 v79, 0
	s_and_saveexec_b64 s[4:5], s[12:13]
	v_mov_b32_e32 v86, v83
	v_ashrrev_i32_e32 v87, 31, v86
	v_lshlrev_b64 v[84:85], 13, v[86:87]
	v_lshl_add_u64 v[84:85], v[10:11], 0, v[84:85]
	global_load_dwordx4 v[76:79], v[84:85], off
	s_or_b64 exec, exec, s[4:5]
	s_waitcnt vmcnt(0)
	ds_write2_b32 v20, v64, v65 offset1:1
	ds_write2_b32 v20, v66, v67 offset0:2 offset1:3
	ds_write2_b32 v21, v68, v69 offset1:1
	ds_write2_b32 v22, v70, v71 offset1:1
	ds_write2_b32 v23, v72, v73 offset1:1
	ds_write2_b32 v24, v74, v75 offset1:1
	ds_write2_b32 v25, v76, v77 offset1:1
	ds_write2_b32 v26, v78, v79 offset1:1
	s_branch .LBB0_195
